# residual epilogues: per-row LayerNorm stats loaded two rows at a time (dwordx4)
# speedup vs baseline: 1.0705x; 1.0060x over previous
.LBB0_39:
	ds_read_b128 v[188:191], v160
	ds_read_b128 v[192:195], v160 offset:32
	ds_read_b128 v[196:199], v161 offset:36864
	ds_read_b128 v[200:203], v161 offset:36896
	ds_read_b128 v[204:207], v160 offset:4608
	ds_read_b128 v[208:211], v160 offset:4640
	ds_read_b128 v[212:215], v161 offset:41472
	ds_read_b128 v[216:219], v161 offset:41504
	s_add_i32 s47, s50, 2
	s_waitcnt lgkmcnt(5)
	v_mfma_f32_32x32x16_bf16 v[50:65], v[188:191], v[196:199], v[50:65]
	s_waitcnt vmcnt(15)
	ds_write_b128 v184, v[66:69] offset:18432
	s_cmp_lt_u32 s47, 41
	s_cselect_b64 s[52:53], -1, 0
	s_and_b64 s[20:21], s[52:53], exec
	s_cselect_b32 s20, 0, 0x1ffffd4
	s_add_i32 s20, s20, s50
	s_lshl_b32 s51, s20, 7
	s_waitcnt lgkmcnt(2)
	v_mfma_f32_32x32x16_bf16 v[34:49], v[188:191], v[212:215], v[34:49]
	s_waitcnt vmcnt(14)
	ds_write_b128 v184, v[74:77] offset:55296
	s_add_i32 s56, s51, 0x280
	s_and_b64 s[20:21], s[52:53], exec
	s_cselect_b32 s21, s27, s41
	s_cselect_b32 s20, s40, s31
	s_and_b32 s21, s21, 0xffff
	s_and_b64 s[52:53], s[52:53], exec
	s_waitcnt lgkmcnt(5)
	v_mfma_f32_32x32x16_bf16 v[16:31], v[204:207], v[196:199], v[16:31]
	s_waitcnt vmcnt(13)
	ds_write_b128 v185, v[70:73] offset:18432
	s_cselect_b32 s53, s30, s46
	s_cselect_b32 s52, s44, s45
	s_and_b32 s53, s53, 0xffff
	s_mov_b32 s54, s22
	s_mov_b32 s55, s23
	s_waitcnt lgkmcnt(4)
	v_mfma_f32_32x32x16_bf16 v[0:15], v[204:207], v[212:215], v[0:15]
	s_waitcnt vmcnt(12)
	ds_write_b128 v185, v[82:85] offset:55296
	s_waitcnt lgkmcnt(8)
	v_mfma_f32_32x32x16_bf16 v[50:65], v[192:195], v[200:203], v[50:65]
	ds_read_b128 v[220:223], v160 offset:64
	ds_read_b128 v[142:145], v160 offset:96
	s_waitcnt vmcnt(11)
	ds_write_b128 v186, v[78:81] offset:18432
	s_waitcnt lgkmcnt(7)
	v_mfma_f32_32x32x16_bf16 v[34:49], v[192:195], v[216:219], v[34:49]
	ds_read_b128 v[154:157], v161 offset:36928
	ds_read_b128 v[138:141], v161 offset:36960
	s_waitcnt vmcnt(10)
	ds_write_b128 v186, v[90:93] offset:55296
	s_waitcnt lgkmcnt(12)
	v_mfma_f32_32x32x16_bf16 v[16:31], v[208:211], v[200:203], v[16:31]
	ds_read_b128 v[146:149], v160 offset:4672
	ds_read_b128 v[130:133], v160 offset:4704
	s_waitcnt vmcnt(9)
	ds_write_b128 v187, v[86:89] offset:18432
	s_waitcnt lgkmcnt(13)
	v_mfma_f32_32x32x16_bf16 v[0:15], v[208:211], v[216:219], v[0:15]
	ds_read_b128 v[150:153], v161 offset:41536
	ds_read_b128 v[134:137], v161 offset:41568
	s_waitcnt vmcnt(8)
	ds_write_b128 v187, v[94:97] offset:55296
	s_waitcnt lgkmcnt(8)
	v_mfma_f32_32x32x16_bf16 v[50:65], v[220:223], v[154:157], v[50:65]
	buffer_load_dwordx4 v[66:69], v180, s[20:23], s56 offen
	s_waitcnt lgkmcnt(2)
	v_mfma_f32_32x32x16_bf16 v[34:49], v[220:223], v[150:153], v[34:49]
	buffer_load_dwordx4 v[74:77], v180, s[52:55], s56 offen
	s_add_i32 s56, s51, 0x2c280
	s_waitcnt lgkmcnt(5)
	v_mfma_f32_32x32x16_bf16 v[16:31], v[146:149], v[154:157], v[16:31]
	buffer_load_dwordx4 v[70:73], v180, s[20:23], s56 offen
	s_waitcnt lgkmcnt(2)
	v_mfma_f32_32x32x16_bf16 v[0:15], v[146:149], v[150:153], v[0:15]
	buffer_load_dwordx4 v[82:85], v180, s[52:55], s56 offen
	s_add_i32 s56, s51, 0x58280
	s_add_i32 s51, s51, 0x84280
	s_waitcnt lgkmcnt(7)
	v_mfma_f32_32x32x16_bf16 v[50:65], v[142:145], v[138:141], v[50:65]
	buffer_load_dwordx4 v[78:81], v180, s[20:23], s56 offen
	s_waitcnt lgkmcnt(1)
	v_mfma_f32_32x32x16_bf16 v[34:49], v[142:145], v[134:137], v[34:49]
	buffer_load_dwordx4 v[90:93], v180, s[52:55], s56 offen
	s_waitcnt lgkmcnt(4)
	v_mfma_f32_32x32x16_bf16 v[16:31], v[130:133], v[138:141], v[16:31]
	buffer_load_dwordx4 v[86:89], v180, s[20:23], s51 offen
	s_waitcnt lgkmcnt(1)
	v_mfma_f32_32x32x16_bf16 v[0:15], v[130:133], v[134:137], v[0:15]
	buffer_load_dwordx4 v[94:97], v180, s[52:55], s51 offen
	s_waitcnt lgkmcnt(0)
	s_barrier
	ds_read_b128 v[188:191], v160 offset:18432
	ds_read_b128 v[192:195], v160 offset:18464
	ds_read_b128 v[196:199], v161 offset:55296
	ds_read_b128 v[200:203], v161 offset:55328
	ds_read_b128 v[204:207], v160 offset:23040
	ds_read_b128 v[208:211], v160 offset:23072
	ds_read_b128 v[212:215], v161 offset:59904
	ds_read_b128 v[216:219], v161 offset:59936
	s_waitcnt lgkmcnt(5)
	v_mfma_f32_32x32x16_bf16 v[50:65], v[188:191], v[196:199], v[50:65]
	s_waitcnt vmcnt(15)
	ds_write_b128 v184, v[98:101]
	s_cmp_lt_u32 s47, 40
	s_cselect_b64 s[52:53], -1, 0
	s_and_b64 s[20:21], s[52:53], exec
	s_cselect_b32 s20, 0, 0x1ffffd4
	s_add_i32 s20, s20, s50
	s_lshl_b32 s56, s20, 7
	s_waitcnt lgkmcnt(2)
	v_mfma_f32_32x32x16_bf16 v[34:49], v[188:191], v[212:215], v[34:49]
	s_waitcnt vmcnt(14)
	ds_write_b128 v184, v[106:109] offset:36864
	s_add_i32 s57, s56, 0x300
	s_and_b64 s[20:21], s[52:53], exec
	s_cselect_b32 s21, s27, s41
	s_cselect_b32 s20, s40, s31
	s_and_b32 s21, s21, 0xffff
	s_and_b64 s[50:51], s[52:53], exec
	s_waitcnt lgkmcnt(5)
	v_mfma_f32_32x32x16_bf16 v[16:31], v[204:207], v[196:199], v[16:31]
	s_waitcnt vmcnt(13)
	ds_write_b128 v185, v[102:105]
	s_cselect_b32 s50, s30, s46
	s_cselect_b32 s52, s44, s45
	s_and_b32 s53, s50, 0xffff
	s_add_i32 s50, s56, 0x2c300
	s_waitcnt lgkmcnt(4)
	v_mfma_f32_32x32x16_bf16 v[0:15], v[204:207], v[212:215], v[0:15]
	s_waitcnt vmcnt(12)
	ds_write_b128 v185, v[114:117] offset:36864
	s_waitcnt lgkmcnt(8)
	v_mfma_f32_32x32x16_bf16 v[50:65], v[192:195], v[200:203], v[50:65]
	ds_read_b128 v[220:223], v160 offset:18496
	ds_read_b128 v[142:145], v160 offset:18528
	s_waitcnt vmcnt(11)
	ds_write_b128 v186, v[110:113]
	s_waitcnt lgkmcnt(7)
	v_mfma_f32_32x32x16_bf16 v[34:49], v[192:195], v[216:219], v[34:49]
	ds_read_b128 v[154:157], v161 offset:55360
	ds_read_b128 v[138:141], v161 offset:55392
	s_waitcnt vmcnt(10)
	ds_write_b128 v186, v[122:125] offset:36864
	s_waitcnt lgkmcnt(12)
	v_mfma_f32_32x32x16_bf16 v[16:31], v[208:211], v[200:203], v[16:31]
	ds_read_b128 v[146:149], v160 offset:23104
	ds_read_b128 v[130:133], v160 offset:23136
	s_waitcnt vmcnt(9)
	ds_write_b128 v187, v[118:121]
	s_waitcnt lgkmcnt(13)
	v_mfma_f32_32x32x16_bf16 v[0:15], v[208:211], v[216:219], v[0:15]
	ds_read_b128 v[150:153], v161 offset:59968
	ds_read_b128 v[134:137], v161 offset:60000
	s_waitcnt vmcnt(8)
	ds_write_b128 v187, v[126:129] offset:36864
	s_waitcnt lgkmcnt(8)
	v_mfma_f32_32x32x16_bf16 v[50:65], v[220:223], v[154:157], v[50:65]
	buffer_load_dwordx4 v[98:101], v180, s[20:23], s57 offen
	s_waitcnt lgkmcnt(2)
	v_mfma_f32_32x32x16_bf16 v[34:49], v[220:223], v[150:153], v[34:49]
	buffer_load_dwordx4 v[106:109], v180, s[52:55], s57 offen
	s_waitcnt lgkmcnt(5)
	v_mfma_f32_32x32x16_bf16 v[16:31], v[146:149], v[154:157], v[16:31]
	buffer_load_dwordx4 v[102:105], v180, s[20:23], s50 offen
	s_waitcnt lgkmcnt(2)
	v_mfma_f32_32x32x16_bf16 v[0:15], v[146:149], v[150:153], v[0:15]
	buffer_load_dwordx4 v[114:117], v180, s[52:55], s50 offen
	s_add_i32 s50, s56, 0x58300
	s_add_i32 s56, s56, 0x84300
	s_waitcnt lgkmcnt(7)
	v_mfma_f32_32x32x16_bf16 v[50:65], v[142:145], v[138:141], v[50:65]
	buffer_load_dwordx4 v[110:113], v180, s[20:23], s50 offen
	s_waitcnt lgkmcnt(1)
	v_mfma_f32_32x32x16_bf16 v[34:49], v[142:145], v[134:137], v[34:49]
	buffer_load_dwordx4 v[122:125], v180, s[52:55], s50 offen
	s_waitcnt lgkmcnt(4)
	v_mfma_f32_32x32x16_bf16 v[16:31], v[130:133], v[138:141], v[16:31]
	buffer_load_dwordx4 v[118:121], v180, s[20:23], s56 offen
	s_waitcnt lgkmcnt(1)
	v_mfma_f32_32x32x16_bf16 v[0:15], v[130:133], v[134:137], v[0:15]
	buffer_load_dwordx4 v[126:129], v180, s[52:55], s56 offen
	s_cmp_gt_u32 s47, 41
	s_mov_b32 s50, s47
	s_waitcnt lgkmcnt(0)
	s_barrier
	s_cbranch_scc0 .LBB0_39
	s_cmpk_lt_i32 s25, 0x80
	s_cselect_b32 s20, s0, 0
	s_add_i32 s21, s20, 0xffffe000
	s_lshr_b32 s21, s21, 10
	s_add_i32 s21, s21, 1
	s_cmpk_gt_i32 s20, 0x1fff
	v_readlane_b32 s30, v232, 27
	s_cselect_b32 s20, s21, 0
	s_mul_i32 s21, s30, 9
	s_add_i32 s20, s20, s21
	v_and_b32_e32 v32, 64, v32
	s_mul_hi_i32 s21, s20, 0x6000
	s_mulk_i32 s20, 0x6000
	s_add_u32 s20, s94, s20
	v_or3_b32 v32, s24, v32, v181
	v_add_u32_e32 v130, s0, v183
	s_addc_u32 s21, s95, s21
	v_lshlrev_b32_e32 v131, 2, v182
	v_or_b32_e32 v132, s38, v32
	s_add_u32 s20, s20, 0x6025000
	v_lshlrev_b32_e32 v142, 2, v32
	v_or_b32_e32 v130, v130, v131
	v_ashrrev_i32_e32 v133, 31, v132
	s_addc_u32 s21, s21, 0
	s_lshl_b64 s[0:1], s[0:1], 12
	v_lshlrev_b32_e32 v136, 3, v130
	v_or_b32_e32 v130, 0x80, v142
	v_lshlrev_b64 v[132:133], 2, v[132:133]
	v_lshl_add_u64 v[138:139], v[32:33], 0, s[38:39]
	s_add_u32 s0, s92, s0
	v_or_b32_e32 v137, v131, v183
	global_load_dword v131, v142, s[20:21]
	v_lshl_add_u64 v[134:135], s[14:15], 0, v[132:133]
	global_load_dword v130, v130, s[20:21]
	v_lshlrev_b64 v[138:139], 2, v[138:139]
	v_readlane_b32 s20, v235, 38
	s_addc_u32 s1, s93, s1
	global_load_dword v134, v[134:135], off
	v_lshl_add_u64 v[140:141], s[14:15], 0, v[138:139]
	v_lshl_add_u64 v[132:133], s[16:17], 0, v[132:133]
	v_lshl_add_u64 v[138:139], s[16:17], 0, v[138:139]
	v_readlane_b32 s21, v235, 39
	v_lshl_or_b32 v135, v137, 12, v142
	global_load_dword v133, v[132:133], off
	v_readlane_b32 s52, v233, 61
	global_load_dword v132, v[138:139], off offset:128
	global_load_dword v32, v[140:141], off offset:128
	v_readlane_b32 s31, v232, 28
	v_readlane_b32 s62, v232, 7
	v_readlane_b32 s63, v232, 8
	s_and_b64 vcc, exec, s[42:43]
	s_mov_b32 s31, s37
	v_readlane_b32 s53, v233, 62
	v_readlane_b32 s56, v232, 1
	v_readlane_b32 s57, v232, 2
	v_readlane_b32 s58, v232, 3
	v_readlane_b32 s59, v232, 4
	v_readlane_b32 s60, v232, 5
	v_readlane_b32 s61, v232, 6
	v_readlane_b32 s64, v232, 9
	v_readlane_b32 s65, v232, 10
	v_readlane_b32 s66, v232, 11
	v_readlane_b32 s67, v232, 12
	v_readlane_b32 s63, v235, 21
	s_movk_i32 s51, 0x3fff
	v_readlane_b32 s62, v232, 31
	v_readlane_b32 s54, v233, 63
	v_readlane_b32 s55, v232, 0
	global_load_dwordx4 v[188:191], v136, s[20:21]
	global_load_dwordx4 v[192:195], v136, s[20:21] offset:16
	global_load_dwordx4 v[196:199], v136, s[20:21] offset:64
	global_load_dwordx4 v[200:203], v136, s[20:21] offset:80
	v_mov_b32_e32 v204, v135
	global_load_dword v212, v204, s[0:1]
	global_load_dword v213, v204, s[0:1] offset:128
	v_or_b32_e32 v205, 0x1000, v135
	global_load_dword v214, v205, s[0:1]
	global_load_dword v215, v205, s[0:1] offset:128
	v_or_b32_e32 v206, 0x2000, v135
	global_load_dword v216, v206, s[0:1]
	global_load_dword v217, v206, s[0:1] offset:128
	v_or_b32_e32 v207, 0x3000, v135
	global_load_dword v218, v207, s[0:1]
	global_load_dword v219, v207, s[0:1] offset:128
	v_or_b32_e32 v208, 0x8000, v135
	global_load_dword v220, v208, s[0:1]
	global_load_dword v221, v208, s[0:1] offset:128
	v_or_b32_e32 v209, 0x9000, v135
	global_load_dword v222, v209, s[0:1]
	global_load_dword v223, v209, s[0:1] offset:128
	v_or_b32_e32 v210, 0xa000, v135
	global_load_dword v224, v210, s[0:1]
	global_load_dword v225, v210, s[0:1] offset:128
	v_or_b32_e32 v211, 0xb000, v135
	global_load_dword v226, v211, s[0:1]
	global_load_dword v227, v211, s[0:1] offset:128
	s_waitcnt vmcnt(14)
	v_sub_f32_e32 v212, v212, v188
	v_sub_f32_e32 v213, v213, v188
	v_mul_f32_e32 v212, v189, v212
	v_mul_f32_e32 v213, v189, v213
	v_fma_f32 v212, v134, v212, v133
	v_fma_f32 v213, v32, v213, v132
	v_mul_f32_e32 v212, 0x3fd744fd, v212
	v_mul_f32_e32 v213, 0x3fd744fd, v213
	v_fmac_f32_e32 v212, v50, v131
	v_fmac_f32_e32 v213, v34, v130
	global_store_dword v204, v212, s[0:1]
	global_store_dword v204, v213, s[0:1] offset:128
	s_waitcnt vmcnt(14)
	v_sub_f32_e32 v214, v214, v190
	v_sub_f32_e32 v215, v215, v190
	v_mul_f32_e32 v214, v191, v214
	v_mul_f32_e32 v215, v191, v215
	v_fma_f32 v214, v134, v214, v133
	v_fma_f32 v215, v32, v215, v132
	v_mul_f32_e32 v214, 0x3fd744fd, v214
	v_mul_f32_e32 v215, 0x3fd744fd, v215
	v_fmac_f32_e32 v214, v51, v131
	v_fmac_f32_e32 v215, v35, v130
	global_store_dword v205, v214, s[0:1]
	global_store_dword v205, v215, s[0:1] offset:128
	s_waitcnt vmcnt(14)
	v_sub_f32_e32 v216, v216, v192
	v_sub_f32_e32 v217, v217, v192
	v_mul_f32_e32 v216, v193, v216
	v_mul_f32_e32 v217, v193, v217
	v_fma_f32 v216, v134, v216, v133
	v_fma_f32 v217, v32, v217, v132
	v_mul_f32_e32 v216, 0x3fd744fd, v216
	v_mul_f32_e32 v217, 0x3fd744fd, v217
	v_fmac_f32_e32 v216, v52, v131
	v_fmac_f32_e32 v217, v36, v130
	global_store_dword v206, v216, s[0:1]
	global_store_dword v206, v217, s[0:1] offset:128
	s_waitcnt vmcnt(14)
	v_sub_f32_e32 v218, v218, v194
	v_sub_f32_e32 v219, v219, v194
	v_mul_f32_e32 v218, v195, v218
	v_mul_f32_e32 v219, v195, v219
	v_fma_f32 v218, v134, v218, v133
	v_fma_f32 v219, v32, v219, v132
	v_mul_f32_e32 v218, 0x3fd744fd, v218
	v_mul_f32_e32 v219, 0x3fd744fd, v219
	v_fmac_f32_e32 v218, v53, v131
	v_fmac_f32_e32 v219, v37, v130
	global_store_dword v207, v218, s[0:1]
	global_store_dword v207, v219, s[0:1] offset:128
	s_waitcnt vmcnt(14)
	v_sub_f32_e32 v220, v220, v196
	v_sub_f32_e32 v221, v221, v196
	v_mul_f32_e32 v220, v197, v220
	v_mul_f32_e32 v221, v197, v221
	v_fma_f32 v220, v134, v220, v133
	v_fma_f32 v221, v32, v221, v132
	v_mul_f32_e32 v220, 0x3fd744fd, v220
	v_mul_f32_e32 v221, 0x3fd744fd, v221
	v_fmac_f32_e32 v220, v54, v131
	v_fmac_f32_e32 v221, v38, v130
	global_store_dword v208, v220, s[0:1]
	global_store_dword v208, v221, s[0:1] offset:128
	s_waitcnt vmcnt(14)
	v_sub_f32_e32 v222, v222, v198
	v_sub_f32_e32 v223, v223, v198
	v_mul_f32_e32 v222, v199, v222
	v_mul_f32_e32 v223, v199, v223
	v_fma_f32 v222, v134, v222, v133
	v_fma_f32 v223, v32, v223, v132
	v_mul_f32_e32 v222, 0x3fd744fd, v222
	v_mul_f32_e32 v223, 0x3fd744fd, v223
	v_fmac_f32_e32 v222, v55, v131
	v_fmac_f32_e32 v223, v39, v130
	global_store_dword v209, v222, s[0:1]
	global_store_dword v209, v223, s[0:1] offset:128
	s_waitcnt vmcnt(14)
	v_sub_f32_e32 v224, v224, v200
	v_sub_f32_e32 v225, v225, v200
	v_mul_f32_e32 v224, v201, v224
	v_mul_f32_e32 v225, v201, v225
	v_fma_f32 v224, v134, v224, v133
	v_fma_f32 v225, v32, v225, v132
	v_mul_f32_e32 v224, 0x3fd744fd, v224
	v_mul_f32_e32 v225, 0x3fd744fd, v225
	v_fmac_f32_e32 v224, v56, v131
	v_fmac_f32_e32 v225, v40, v130
	global_store_dword v210, v224, s[0:1]
	global_store_dword v210, v225, s[0:1] offset:128
	s_waitcnt vmcnt(14)
	v_sub_f32_e32 v226, v226, v202
	v_sub_f32_e32 v227, v227, v202
	v_mul_f32_e32 v226, v203, v226
	v_mul_f32_e32 v227, v203, v227
	v_fma_f32 v226, v134, v226, v133
	v_fma_f32 v227, v32, v227, v132
	v_mul_f32_e32 v226, 0x3fd744fd, v226
	v_mul_f32_e32 v227, 0x3fd744fd, v227
	v_fmac_f32_e32 v226, v57, v131
	v_fmac_f32_e32 v227, v41, v130
	global_store_dword v211, v226, s[0:1]
	global_store_dword v211, v227, s[0:1] offset:128
	global_load_dwordx4 v[188:191], v136, s[20:21] offset:128
	global_load_dwordx4 v[192:195], v136, s[20:21] offset:144
	global_load_dwordx4 v[196:199], v136, s[20:21] offset:192
	global_load_dwordx4 v[200:203], v136, s[20:21] offset:208
	v_or_b32_e32 v204, 0x10000, v135
	global_load_dword v212, v204, s[0:1]
	global_load_dword v213, v204, s[0:1] offset:128
	v_or_b32_e32 v205, 0x11000, v135
	global_load_dword v214, v205, s[0:1]
	global_load_dword v215, v205, s[0:1] offset:128
	v_or_b32_e32 v206, 0x12000, v135
	global_load_dword v216, v206, s[0:1]
	global_load_dword v217, v206, s[0:1] offset:128
	v_or_b32_e32 v207, 0x13000, v135
	global_load_dword v218, v207, s[0:1]
	global_load_dword v219, v207, s[0:1] offset:128
	v_or_b32_e32 v208, 0x18000, v135
	global_load_dword v220, v208, s[0:1]
	global_load_dword v221, v208, s[0:1] offset:128
	v_or_b32_e32 v209, 0x19000, v135
	global_load_dword v222, v209, s[0:1]
	global_load_dword v223, v209, s[0:1] offset:128
	v_or_b32_e32 v210, 0x1a000, v135
	global_load_dword v224, v210, s[0:1]
	global_load_dword v225, v210, s[0:1] offset:128
	v_or_b32_e32 v211, 0x1b000, v135
	global_load_dword v226, v211, s[0:1]
	global_load_dword v227, v211, s[0:1] offset:128
	s_waitcnt vmcnt(14)
	v_sub_f32_e32 v212, v212, v188
	v_sub_f32_e32 v213, v213, v188
	v_mul_f32_e32 v212, v189, v212
	v_mul_f32_e32 v213, v189, v213
	v_fma_f32 v212, v134, v212, v133
	v_fma_f32 v213, v32, v213, v132
	v_mul_f32_e32 v212, 0x3fd744fd, v212
	v_mul_f32_e32 v213, 0x3fd744fd, v213
	v_fmac_f32_e32 v212, v58, v131
	v_fmac_f32_e32 v213, v42, v130
	global_store_dword v204, v212, s[0:1]
	global_store_dword v204, v213, s[0:1] offset:128
	s_waitcnt vmcnt(14)
	v_sub_f32_e32 v214, v214, v190
	v_sub_f32_e32 v215, v215, v190
	v_mul_f32_e32 v214, v191, v214
	v_mul_f32_e32 v215, v191, v215
	v_fma_f32 v214, v134, v214, v133
	v_fma_f32 v215, v32, v215, v132
	v_mul_f32_e32 v214, 0x3fd744fd, v214
	v_mul_f32_e32 v215, 0x3fd744fd, v215
	v_fmac_f32_e32 v214, v59, v131
	v_fmac_f32_e32 v215, v43, v130
	global_store_dword v205, v214, s[0:1]
	global_store_dword v205, v215, s[0:1] offset:128
	s_waitcnt vmcnt(14)
	v_sub_f32_e32 v216, v216, v192
	v_sub_f32_e32 v217, v217, v192
	v_mul_f32_e32 v216, v193, v216
	v_mul_f32_e32 v217, v193, v217
	v_fma_f32 v216, v134, v216, v133
	v_fma_f32 v217, v32, v217, v132
	v_mul_f32_e32 v216, 0x3fd744fd, v216
	v_mul_f32_e32 v217, 0x3fd744fd, v217
	v_fmac_f32_e32 v216, v60, v131
	v_fmac_f32_e32 v217, v44, v130
	global_store_dword v206, v216, s[0:1]
	global_store_dword v206, v217, s[0:1] offset:128
	s_waitcnt vmcnt(14)
	v_sub_f32_e32 v218, v218, v194
	v_sub_f32_e32 v219, v219, v194
	v_mul_f32_e32 v218, v195, v218
	v_mul_f32_e32 v219, v195, v219
	v_fma_f32 v218, v134, v218, v133
	v_fma_f32 v219, v32, v219, v132
	v_mul_f32_e32 v218, 0x3fd744fd, v218
	v_mul_f32_e32 v219, 0x3fd744fd, v219
	v_fmac_f32_e32 v218, v61, v131
	v_fmac_f32_e32 v219, v45, v130
	global_store_dword v207, v218, s[0:1]
	global_store_dword v207, v219, s[0:1] offset:128
	s_waitcnt vmcnt(14)
	v_sub_f32_e32 v220, v220, v196
	v_sub_f32_e32 v221, v221, v196
	v_mul_f32_e32 v220, v197, v220
	v_mul_f32_e32 v221, v197, v221
	v_fma_f32 v220, v134, v220, v133
	v_fma_f32 v221, v32, v221, v132
	v_mul_f32_e32 v220, 0x3fd744fd, v220
	v_mul_f32_e32 v221, 0x3fd744fd, v221
	v_fmac_f32_e32 v220, v62, v131
	v_fmac_f32_e32 v221, v46, v130
	global_store_dword v208, v220, s[0:1]
	global_store_dword v208, v221, s[0:1] offset:128
	s_waitcnt vmcnt(14)
	v_sub_f32_e32 v222, v222, v198
	v_sub_f32_e32 v223, v223, v198
	v_mul_f32_e32 v222, v199, v222
	v_mul_f32_e32 v223, v199, v223
	v_fma_f32 v222, v134, v222, v133
	v_fma_f32 v223, v32, v223, v132
	v_mul_f32_e32 v222, 0x3fd744fd, v222
	v_mul_f32_e32 v223, 0x3fd744fd, v223
	v_fmac_f32_e32 v222, v63, v131
	v_fmac_f32_e32 v223, v47, v130
	global_store_dword v209, v222, s[0:1]
	global_store_dword v209, v223, s[0:1] offset:128
	s_waitcnt vmcnt(14)
	v_sub_f32_e32 v224, v224, v200
	v_sub_f32_e32 v225, v225, v200
	v_mul_f32_e32 v224, v201, v224
	v_mul_f32_e32 v225, v201, v225
	v_fma_f32 v224, v134, v224, v133
	v_fma_f32 v225, v32, v225, v132
	v_mul_f32_e32 v224, 0x3fd744fd, v224
	v_mul_f32_e32 v225, 0x3fd744fd, v225
	v_fmac_f32_e32 v224, v64, v131
	v_fmac_f32_e32 v225, v48, v130
	global_store_dword v210, v224, s[0:1]
	global_store_dword v210, v225, s[0:1] offset:128
	s_waitcnt vmcnt(14)
	v_sub_f32_e32 v226, v226, v202
	v_sub_f32_e32 v227, v227, v202
	v_mul_f32_e32 v226, v203, v226
	v_mul_f32_e32 v227, v203, v227
	v_fma_f32 v226, v134, v226, v133
	v_fma_f32 v227, v32, v227, v132
	v_mul_f32_e32 v226, 0x3fd744fd, v226
	v_mul_f32_e32 v227, 0x3fd744fd, v227
	v_fmac_f32_e32 v226, v65, v131
	v_fmac_f32_e32 v227, v49, v130
	global_store_dword v211, v226, s[0:1]
	global_store_dword v211, v227, s[0:1] offset:128
	global_load_dwordx4 v[188:191], v136, s[20:21] offset:256
	global_load_dwordx4 v[192:195], v136, s[20:21] offset:272
	global_load_dwordx4 v[196:199], v136, s[20:21] offset:320
	global_load_dwordx4 v[200:203], v136, s[20:21] offset:336
	v_or_b32_e32 v204, 0x20000, v135
	global_load_dword v212, v204, s[0:1]
	global_load_dword v213, v204, s[0:1] offset:128
	v_or_b32_e32 v205, 0x21000, v135
	global_load_dword v214, v205, s[0:1]
	global_load_dword v215, v205, s[0:1] offset:128
	v_or_b32_e32 v206, 0x22000, v135
	global_load_dword v216, v206, s[0:1]
	global_load_dword v217, v206, s[0:1] offset:128
	v_or_b32_e32 v207, 0x23000, v135
	global_load_dword v218, v207, s[0:1]
	global_load_dword v219, v207, s[0:1] offset:128
	v_or_b32_e32 v208, 0x28000, v135
	global_load_dword v220, v208, s[0:1]
	global_load_dword v221, v208, s[0:1] offset:128
	v_or_b32_e32 v209, 0x29000, v135
	global_load_dword v222, v209, s[0:1]
	global_load_dword v223, v209, s[0:1] offset:128
	v_or_b32_e32 v210, 0x2a000, v135
	global_load_dword v224, v210, s[0:1]
	global_load_dword v225, v210, s[0:1] offset:128
	v_or_b32_e32 v211, 0x2b000, v135
	global_load_dword v226, v211, s[0:1]
	global_load_dword v227, v211, s[0:1] offset:128
	s_waitcnt vmcnt(14)
	v_sub_f32_e32 v212, v212, v188
	v_sub_f32_e32 v213, v213, v188
	v_mul_f32_e32 v212, v189, v212
	v_mul_f32_e32 v213, v189, v213
	v_fma_f32 v212, v134, v212, v133
	v_fma_f32 v213, v32, v213, v132
	v_mul_f32_e32 v212, 0x3fd744fd, v212
	v_mul_f32_e32 v213, 0x3fd744fd, v213
	v_fmac_f32_e32 v212, v16, v131
	v_fmac_f32_e32 v213, v0, v130
	global_store_dword v204, v212, s[0:1]
	global_store_dword v204, v213, s[0:1] offset:128
	s_waitcnt vmcnt(14)
	v_sub_f32_e32 v214, v214, v190
	v_sub_f32_e32 v215, v215, v190
	v_mul_f32_e32 v214, v191, v214
	v_mul_f32_e32 v215, v191, v215
	v_fma_f32 v214, v134, v214, v133
	v_fma_f32 v215, v32, v215, v132
	v_mul_f32_e32 v214, 0x3fd744fd, v214
	v_mul_f32_e32 v215, 0x3fd744fd, v215
	v_fmac_f32_e32 v214, v17, v131
	v_fmac_f32_e32 v215, v1, v130
	global_store_dword v205, v214, s[0:1]
	global_store_dword v205, v215, s[0:1] offset:128
	s_waitcnt vmcnt(14)
	v_sub_f32_e32 v216, v216, v192
	v_sub_f32_e32 v217, v217, v192
	v_mul_f32_e32 v216, v193, v216
	v_mul_f32_e32 v217, v193, v217
	v_fma_f32 v216, v134, v216, v133
	v_fma_f32 v217, v32, v217, v132
	v_mul_f32_e32 v216, 0x3fd744fd, v216
	v_mul_f32_e32 v217, 0x3fd744fd, v217
	v_fmac_f32_e32 v216, v18, v131
	v_fmac_f32_e32 v217, v2, v130
	global_store_dword v206, v216, s[0:1]
	global_store_dword v206, v217, s[0:1] offset:128
	s_waitcnt vmcnt(14)
	v_sub_f32_e32 v218, v218, v194
	v_sub_f32_e32 v219, v219, v194
	v_mul_f32_e32 v218, v195, v218
	v_mul_f32_e32 v219, v195, v219
	v_fma_f32 v218, v134, v218, v133
	v_fma_f32 v219, v32, v219, v132
	v_mul_f32_e32 v218, 0x3fd744fd, v218
	v_mul_f32_e32 v219, 0x3fd744fd, v219
	v_fmac_f32_e32 v218, v19, v131
	v_fmac_f32_e32 v219, v3, v130
	global_store_dword v207, v218, s[0:1]
	global_store_dword v207, v219, s[0:1] offset:128
	s_waitcnt vmcnt(14)
	v_sub_f32_e32 v220, v220, v196
	v_sub_f32_e32 v221, v221, v196
	v_mul_f32_e32 v220, v197, v220
	v_mul_f32_e32 v221, v197, v221
	v_fma_f32 v220, v134, v220, v133
	v_fma_f32 v221, v32, v221, v132
	v_mul_f32_e32 v220, 0x3fd744fd, v220
	v_mul_f32_e32 v221, 0x3fd744fd, v221
	v_fmac_f32_e32 v220, v20, v131
	v_fmac_f32_e32 v221, v4, v130
	global_store_dword v208, v220, s[0:1]
	global_store_dword v208, v221, s[0:1] offset:128
	s_waitcnt vmcnt(14)
	v_sub_f32_e32 v222, v222, v198
	v_sub_f32_e32 v223, v223, v198
	v_mul_f32_e32 v222, v199, v222
	v_mul_f32_e32 v223, v199, v223
	v_fma_f32 v222, v134, v222, v133
	v_fma_f32 v223, v32, v223, v132
	v_mul_f32_e32 v222, 0x3fd744fd, v222
	v_mul_f32_e32 v223, 0x3fd744fd, v223
	v_fmac_f32_e32 v222, v21, v131
	v_fmac_f32_e32 v223, v5, v130
	global_store_dword v209, v222, s[0:1]
	global_store_dword v209, v223, s[0:1] offset:128
	s_waitcnt vmcnt(14)
	v_sub_f32_e32 v224, v224, v200
	v_sub_f32_e32 v225, v225, v200
	v_mul_f32_e32 v224, v201, v224
	v_mul_f32_e32 v225, v201, v225
	v_fma_f32 v224, v134, v224, v133
	v_fma_f32 v225, v32, v225, v132
	v_mul_f32_e32 v224, 0x3fd744fd, v224
	v_mul_f32_e32 v225, 0x3fd744fd, v225
	v_fmac_f32_e32 v224, v22, v131
	v_fmac_f32_e32 v225, v6, v130
	global_store_dword v210, v224, s[0:1]
	global_store_dword v210, v225, s[0:1] offset:128
	s_waitcnt vmcnt(14)
	v_sub_f32_e32 v226, v226, v202
	v_sub_f32_e32 v227, v227, v202
	v_mul_f32_e32 v226, v203, v226
	v_mul_f32_e32 v227, v203, v227
	v_fma_f32 v226, v134, v226, v133
	v_fma_f32 v227, v32, v227, v132
	v_mul_f32_e32 v226, 0x3fd744fd, v226
	v_mul_f32_e32 v227, 0x3fd744fd, v227
	v_fmac_f32_e32 v226, v23, v131
	v_fmac_f32_e32 v227, v7, v130
	global_store_dword v211, v226, s[0:1]
	global_store_dword v211, v227, s[0:1] offset:128
	global_load_dwordx4 v[188:191], v136, s[20:21] offset:384
	global_load_dwordx4 v[192:195], v136, s[20:21] offset:400
	global_load_dwordx4 v[196:199], v136, s[20:21] offset:448
	global_load_dwordx4 v[200:203], v136, s[20:21] offset:464
	v_or_b32_e32 v204, 0x30000, v135
	global_load_dword v212, v204, s[0:1]
	global_load_dword v213, v204, s[0:1] offset:128
	v_or_b32_e32 v205, 0x31000, v135
	global_load_dword v214, v205, s[0:1]
	global_load_dword v215, v205, s[0:1] offset:128
	v_or_b32_e32 v206, 0x32000, v135
	global_load_dword v216, v206, s[0:1]
	global_load_dword v217, v206, s[0:1] offset:128
	v_or_b32_e32 v207, 0x33000, v135
	global_load_dword v218, v207, s[0:1]
	global_load_dword v219, v207, s[0:1] offset:128
	v_or_b32_e32 v208, 0x38000, v135
	global_load_dword v220, v208, s[0:1]
	global_load_dword v221, v208, s[0:1] offset:128
	v_or_b32_e32 v209, 0x39000, v135
	global_load_dword v222, v209, s[0:1]
	global_load_dword v223, v209, s[0:1] offset:128
	v_or_b32_e32 v210, 0x3a000, v135
	global_load_dword v224, v210, s[0:1]
	global_load_dword v225, v210, s[0:1] offset:128
	v_or_b32_e32 v211, 0x3b000, v135
	global_load_dword v226, v211, s[0:1]
	global_load_dword v227, v211, s[0:1] offset:128
	s_waitcnt vmcnt(14)
	v_sub_f32_e32 v212, v212, v188
	v_sub_f32_e32 v213, v213, v188
	v_mul_f32_e32 v212, v189, v212
	v_mul_f32_e32 v213, v189, v213
	v_fma_f32 v212, v134, v212, v133
	v_fma_f32 v213, v32, v213, v132
	v_mul_f32_e32 v212, 0x3fd744fd, v212
	v_mul_f32_e32 v213, 0x3fd744fd, v213
	v_fmac_f32_e32 v212, v24, v131
	v_fmac_f32_e32 v213, v8, v130
	global_store_dword v204, v212, s[0:1]
	global_store_dword v204, v213, s[0:1] offset:128
	s_waitcnt vmcnt(14)
	v_sub_f32_e32 v214, v214, v190
	v_sub_f32_e32 v215, v215, v190
	v_mul_f32_e32 v214, v191, v214
	v_mul_f32_e32 v215, v191, v215
	v_fma_f32 v214, v134, v214, v133
	v_fma_f32 v215, v32, v215, v132
	v_mul_f32_e32 v214, 0x3fd744fd, v214
	v_mul_f32_e32 v215, 0x3fd744fd, v215
	v_fmac_f32_e32 v214, v25, v131
	v_fmac_f32_e32 v215, v9, v130
	global_store_dword v205, v214, s[0:1]
	global_store_dword v205, v215, s[0:1] offset:128
	s_waitcnt vmcnt(14)
	v_sub_f32_e32 v216, v216, v192
	v_sub_f32_e32 v217, v217, v192
	v_mul_f32_e32 v216, v193, v216
	v_mul_f32_e32 v217, v193, v217
	v_fma_f32 v216, v134, v216, v133
	v_fma_f32 v217, v32, v217, v132
	v_mul_f32_e32 v216, 0x3fd744fd, v216
	v_mul_f32_e32 v217, 0x3fd744fd, v217
	v_fmac_f32_e32 v216, v26, v131
	v_fmac_f32_e32 v217, v10, v130
	global_store_dword v206, v216, s[0:1]
	global_store_dword v206, v217, s[0:1] offset:128
	s_waitcnt vmcnt(14)
	v_sub_f32_e32 v218, v218, v194
	v_sub_f32_e32 v219, v219, v194
	v_mul_f32_e32 v218, v195, v218
	v_mul_f32_e32 v219, v195, v219
	v_fma_f32 v218, v134, v218, v133
	v_fma_f32 v219, v32, v219, v132
	v_mul_f32_e32 v218, 0x3fd744fd, v218
	v_mul_f32_e32 v219, 0x3fd744fd, v219
	v_fmac_f32_e32 v218, v27, v131
	v_fmac_f32_e32 v219, v11, v130
	global_store_dword v207, v218, s[0:1]
	global_store_dword v207, v219, s[0:1] offset:128
	s_waitcnt vmcnt(14)
	v_sub_f32_e32 v220, v220, v196
	v_sub_f32_e32 v221, v221, v196
	v_mul_f32_e32 v220, v197, v220
	v_mul_f32_e32 v221, v197, v221
	v_fma_f32 v220, v134, v220, v133
	v_fma_f32 v221, v32, v221, v132
	v_mul_f32_e32 v220, 0x3fd744fd, v220
	v_mul_f32_e32 v221, 0x3fd744fd, v221
	v_fmac_f32_e32 v220, v28, v131
	v_fmac_f32_e32 v221, v12, v130
	global_store_dword v208, v220, s[0:1]
	global_store_dword v208, v221, s[0:1] offset:128
	s_waitcnt vmcnt(14)
	v_sub_f32_e32 v222, v222, v198
	v_sub_f32_e32 v223, v223, v198
	v_mul_f32_e32 v222, v199, v222
	v_mul_f32_e32 v223, v199, v223
	v_fma_f32 v222, v134, v222, v133
	v_fma_f32 v223, v32, v223, v132
	v_mul_f32_e32 v222, 0x3fd744fd, v222
	v_mul_f32_e32 v223, 0x3fd744fd, v223
	v_fmac_f32_e32 v222, v29, v131
	v_fmac_f32_e32 v223, v13, v130
	global_store_dword v209, v222, s[0:1]
	global_store_dword v209, v223, s[0:1] offset:128
	s_waitcnt vmcnt(14)
	v_sub_f32_e32 v224, v224, v200
	v_sub_f32_e32 v225, v225, v200
	v_mul_f32_e32 v224, v201, v224
	v_mul_f32_e32 v225, v201, v225
	v_fma_f32 v224, v134, v224, v133
	v_fma_f32 v225, v32, v225, v132
	v_mul_f32_e32 v224, 0x3fd744fd, v224
	v_mul_f32_e32 v225, 0x3fd744fd, v225
	v_fmac_f32_e32 v224, v30, v131
	v_fmac_f32_e32 v225, v14, v130
	global_store_dword v210, v224, s[0:1]
	global_store_dword v210, v225, s[0:1] offset:128
	s_waitcnt vmcnt(14)
	v_sub_f32_e32 v226, v226, v202
	v_sub_f32_e32 v227, v227, v202
	v_mul_f32_e32 v226, v203, v226
	v_mul_f32_e32 v227, v203, v227
	v_fma_f32 v226, v134, v226, v133
	v_fma_f32 v227, v32, v227, v132
	v_mul_f32_e32 v226, 0x3fd744fd, v226
	v_mul_f32_e32 v227, 0x3fd744fd, v227
	v_fmac_f32_e32 v226, v31, v131
	v_fmac_f32_e32 v227, v15, v130
	global_store_dword v211, v226, s[0:1]
	global_store_dword v211, v227, s[0:1] offset:128
	s_mov_b64 s[20:21], 0
	s_cbranch_vccz .LBB0_34

.LBB0_83:
	v_add_u32_e32 v32, s28, v182
	v_lshlrev_b32_e32 v135, 2, v181
	v_or_b32_e32 v32, v32, v135
	v_readlane_b32 s24, v235, 38
	v_lshlrev_b32_e32 v32, 3, v32
	v_readlane_b32 s25, v235, 39
	s_and_b64 vcc, exec, s[38:39]
	v_readlane_b32 s63, v235, 21
	v_lshl_add_u64 v[130:131], s[24:25], 0, v[32:33]
	v_readlane_b32 s62, v232, 31
	v_or_b32_e32 v32, v135, v182
	v_lshl_or_b32 v32, v32, 12, v134
	s_add_u32 s20, s92, s20
	s_addc_u32 s21, s93, s21
	v_mov_b32_e32 v188, 0
	v_mov_b32_e32 v189, 1.0
	v_mov_b32_e32 v190, 0
	v_mov_b32_e32 v191, 1.0
	v_mov_b32_e32 v192, 0
	v_mov_b32_e32 v193, 1.0
	v_mov_b32_e32 v194, 0
	v_mov_b32_e32 v195, 1.0
	v_mov_b32_e32 v196, 0
	v_mov_b32_e32 v197, 1.0
	v_mov_b32_e32 v198, 0
	v_mov_b32_e32 v199, 1.0
	v_mov_b32_e32 v200, 0
	v_mov_b32_e32 v201, 1.0
	v_mov_b32_e32 v202, 0
	v_mov_b32_e32 v203, 1.0
	s_and_b64 vcc, exec, s[38:39]
	s_cbranch_vccnz .Lres77_ns0
	global_load_dwordx4 v[188:191], v[130:131], off
	global_load_dwordx4 v[192:195], v[130:131], off offset:16
	global_load_dwordx4 v[196:199], v[130:131], off offset:64
	global_load_dwordx4 v[200:203], v[130:131], off offset:80
.Lres77_ns0:
	v_mov_b32_e32 v204, v32
	global_load_dword v212, v204, s[0:1]
	global_load_dword v213, v204, s[0:1] offset:128
	v_or_b32_e32 v205, 0x1000, v32
	global_load_dword v214, v205, s[0:1]
	global_load_dword v215, v205, s[0:1] offset:128
	v_or_b32_e32 v206, 0x2000, v32
	global_load_dword v216, v206, s[0:1]
	global_load_dword v217, v206, s[0:1] offset:128
	v_or_b32_e32 v207, 0x3000, v32
	global_load_dword v218, v207, s[0:1]
	global_load_dword v219, v207, s[0:1] offset:128
	v_or_b32_e32 v208, 0x8000, v32
	global_load_dword v220, v208, s[0:1]
	global_load_dword v221, v208, s[0:1] offset:128
	v_or_b32_e32 v209, 0x9000, v32
	global_load_dword v222, v209, s[0:1]
	global_load_dword v223, v209, s[0:1] offset:128
	v_or_b32_e32 v210, 0xa000, v32
	global_load_dword v224, v210, s[0:1]
	global_load_dword v225, v210, s[0:1] offset:128
	v_or_b32_e32 v211, 0xb000, v32
	global_load_dword v226, v211, s[0:1]
	global_load_dword v227, v211, s[0:1] offset:128
	s_waitcnt vmcnt(14)
	v_sub_f32_e32 v212, v212, v188
	v_sub_f32_e32 v213, v213, v188
	v_mul_f32_e32 v212, v189, v212
	v_mul_f32_e32 v213, v189, v213
	v_fma_f32 v212, v141, v212, v138
	v_fma_f32 v213, v139, v213, v140
	v_mul_f32_e32 v212, 0x3fd744fd, v212
	v_mul_f32_e32 v213, 0x3fd744fd, v213
	v_fmac_f32_e32 v212, v50, v137
	v_fmac_f32_e32 v213, v34, v136
	global_store_dword v204, v212, s[20:21]
	global_store_dword v204, v213, s[20:21] offset:128
	s_waitcnt vmcnt(14)
	v_sub_f32_e32 v214, v214, v190
	v_sub_f32_e32 v215, v215, v190
	v_mul_f32_e32 v214, v191, v214
	v_mul_f32_e32 v215, v191, v215
	v_fma_f32 v214, v141, v214, v138
	v_fma_f32 v215, v139, v215, v140
	v_mul_f32_e32 v214, 0x3fd744fd, v214
	v_mul_f32_e32 v215, 0x3fd744fd, v215
	v_fmac_f32_e32 v214, v51, v137
	v_fmac_f32_e32 v215, v35, v136
	global_store_dword v205, v214, s[20:21]
	global_store_dword v205, v215, s[20:21] offset:128
	s_waitcnt vmcnt(14)
	v_sub_f32_e32 v216, v216, v192
	v_sub_f32_e32 v217, v217, v192
	v_mul_f32_e32 v216, v193, v216
	v_mul_f32_e32 v217, v193, v217
	v_fma_f32 v216, v141, v216, v138
	v_fma_f32 v217, v139, v217, v140
	v_mul_f32_e32 v216, 0x3fd744fd, v216
	v_mul_f32_e32 v217, 0x3fd744fd, v217
	v_fmac_f32_e32 v216, v52, v137
	v_fmac_f32_e32 v217, v36, v136
	global_store_dword v206, v216, s[20:21]
	global_store_dword v206, v217, s[20:21] offset:128
	s_waitcnt vmcnt(14)
	v_sub_f32_e32 v218, v218, v194
	v_sub_f32_e32 v219, v219, v194
	v_mul_f32_e32 v218, v195, v218
	v_mul_f32_e32 v219, v195, v219
	v_fma_f32 v218, v141, v218, v138
	v_fma_f32 v219, v139, v219, v140
	v_mul_f32_e32 v218, 0x3fd744fd, v218
	v_mul_f32_e32 v219, 0x3fd744fd, v219
	v_fmac_f32_e32 v218, v53, v137
	v_fmac_f32_e32 v219, v37, v136
	global_store_dword v207, v218, s[20:21]
	global_store_dword v207, v219, s[20:21] offset:128
	s_waitcnt vmcnt(14)
	v_sub_f32_e32 v220, v220, v196
	v_sub_f32_e32 v221, v221, v196
	v_mul_f32_e32 v220, v197, v220
	v_mul_f32_e32 v221, v197, v221
	v_fma_f32 v220, v141, v220, v138
	v_fma_f32 v221, v139, v221, v140
	v_mul_f32_e32 v220, 0x3fd744fd, v220
	v_mul_f32_e32 v221, 0x3fd744fd, v221
	v_fmac_f32_e32 v220, v54, v137
	v_fmac_f32_e32 v221, v38, v136
	global_store_dword v208, v220, s[20:21]
	global_store_dword v208, v221, s[20:21] offset:128
	s_waitcnt vmcnt(14)
	v_sub_f32_e32 v222, v222, v198
	v_sub_f32_e32 v223, v223, v198
	v_mul_f32_e32 v222, v199, v222
	v_mul_f32_e32 v223, v199, v223
	v_fma_f32 v222, v141, v222, v138
	v_fma_f32 v223, v139, v223, v140
	v_mul_f32_e32 v222, 0x3fd744fd, v222
	v_mul_f32_e32 v223, 0x3fd744fd, v223
	v_fmac_f32_e32 v222, v55, v137
	v_fmac_f32_e32 v223, v39, v136
	global_store_dword v209, v222, s[20:21]
	global_store_dword v209, v223, s[20:21] offset:128
	s_waitcnt vmcnt(14)
	v_sub_f32_e32 v224, v224, v200
	v_sub_f32_e32 v225, v225, v200
	v_mul_f32_e32 v224, v201, v224
	v_mul_f32_e32 v225, v201, v225
	v_fma_f32 v224, v141, v224, v138
	v_fma_f32 v225, v139, v225, v140
	v_mul_f32_e32 v224, 0x3fd744fd, v224
	v_mul_f32_e32 v225, 0x3fd744fd, v225
	v_fmac_f32_e32 v224, v56, v137
	v_fmac_f32_e32 v225, v40, v136
	global_store_dword v210, v224, s[20:21]
	global_store_dword v210, v225, s[20:21] offset:128
	s_waitcnt vmcnt(14)
	v_sub_f32_e32 v226, v226, v202
	v_sub_f32_e32 v227, v227, v202
	v_mul_f32_e32 v226, v203, v226
	v_mul_f32_e32 v227, v203, v227
	v_fma_f32 v226, v141, v226, v138
	v_fma_f32 v227, v139, v227, v140
	v_mul_f32_e32 v226, 0x3fd744fd, v226
	v_mul_f32_e32 v227, 0x3fd744fd, v227
	v_fmac_f32_e32 v226, v57, v137
	v_fmac_f32_e32 v227, v41, v136
	global_store_dword v211, v226, s[20:21]
	global_store_dword v211, v227, s[20:21] offset:128
	v_mov_b32_e32 v188, 0
	v_mov_b32_e32 v189, 1.0
	v_mov_b32_e32 v190, 0
	v_mov_b32_e32 v191, 1.0
	v_mov_b32_e32 v192, 0
	v_mov_b32_e32 v193, 1.0
	v_mov_b32_e32 v194, 0
	v_mov_b32_e32 v195, 1.0
	v_mov_b32_e32 v196, 0
	v_mov_b32_e32 v197, 1.0
	v_mov_b32_e32 v198, 0
	v_mov_b32_e32 v199, 1.0
	v_mov_b32_e32 v200, 0
	v_mov_b32_e32 v201, 1.0
	v_mov_b32_e32 v202, 0
	v_mov_b32_e32 v203, 1.0
	s_and_b64 vcc, exec, s[38:39]
	s_cbranch_vccnz .Lres77_ns1
	global_load_dwordx4 v[188:191], v[130:131], off offset:128
	global_load_dwordx4 v[192:195], v[130:131], off offset:144
	global_load_dwordx4 v[196:199], v[130:131], off offset:192
	global_load_dwordx4 v[200:203], v[130:131], off offset:208
.Lres77_ns1:
	v_or_b32_e32 v204, 0x10000, v32
	global_load_dword v212, v204, s[0:1]
	global_load_dword v213, v204, s[0:1] offset:128
	v_or_b32_e32 v205, 0x11000, v32
	global_load_dword v214, v205, s[0:1]
	global_load_dword v215, v205, s[0:1] offset:128
	v_or_b32_e32 v206, 0x12000, v32
	global_load_dword v216, v206, s[0:1]
	global_load_dword v217, v206, s[0:1] offset:128
	v_or_b32_e32 v207, 0x13000, v32
	global_load_dword v218, v207, s[0:1]
	global_load_dword v219, v207, s[0:1] offset:128
	v_or_b32_e32 v208, 0x18000, v32
	global_load_dword v220, v208, s[0:1]
	global_load_dword v221, v208, s[0:1] offset:128
	v_or_b32_e32 v209, 0x19000, v32
	global_load_dword v222, v209, s[0:1]
	global_load_dword v223, v209, s[0:1] offset:128
	v_or_b32_e32 v210, 0x1a000, v32
	global_load_dword v224, v210, s[0:1]
	global_load_dword v225, v210, s[0:1] offset:128
	v_or_b32_e32 v211, 0x1b000, v32
	global_load_dword v226, v211, s[0:1]
	global_load_dword v227, v211, s[0:1] offset:128
	s_waitcnt vmcnt(14)
	v_sub_f32_e32 v212, v212, v188
	v_sub_f32_e32 v213, v213, v188
	v_mul_f32_e32 v212, v189, v212
	v_mul_f32_e32 v213, v189, v213
	v_fma_f32 v212, v141, v212, v138
	v_fma_f32 v213, v139, v213, v140
	v_mul_f32_e32 v212, 0x3fd744fd, v212
	v_mul_f32_e32 v213, 0x3fd744fd, v213
	v_fmac_f32_e32 v212, v58, v137
	v_fmac_f32_e32 v213, v42, v136
	global_store_dword v204, v212, s[20:21]
	global_store_dword v204, v213, s[20:21] offset:128
	s_waitcnt vmcnt(14)
	v_sub_f32_e32 v214, v214, v190
	v_sub_f32_e32 v215, v215, v190
	v_mul_f32_e32 v214, v191, v214
	v_mul_f32_e32 v215, v191, v215
	v_fma_f32 v214, v141, v214, v138
	v_fma_f32 v215, v139, v215, v140
	v_mul_f32_e32 v214, 0x3fd744fd, v214
	v_mul_f32_e32 v215, 0x3fd744fd, v215
	v_fmac_f32_e32 v214, v59, v137
	v_fmac_f32_e32 v215, v43, v136
	global_store_dword v205, v214, s[20:21]
	global_store_dword v205, v215, s[20:21] offset:128
	s_waitcnt vmcnt(14)
	v_sub_f32_e32 v216, v216, v192
	v_sub_f32_e32 v217, v217, v192
	v_mul_f32_e32 v216, v193, v216
	v_mul_f32_e32 v217, v193, v217
	v_fma_f32 v216, v141, v216, v138
	v_fma_f32 v217, v139, v217, v140
	v_mul_f32_e32 v216, 0x3fd744fd, v216
	v_mul_f32_e32 v217, 0x3fd744fd, v217
	v_fmac_f32_e32 v216, v60, v137
	v_fmac_f32_e32 v217, v44, v136
	global_store_dword v206, v216, s[20:21]
	global_store_dword v206, v217, s[20:21] offset:128
	s_waitcnt vmcnt(14)
	v_sub_f32_e32 v218, v218, v194
	v_sub_f32_e32 v219, v219, v194
	v_mul_f32_e32 v218, v195, v218
	v_mul_f32_e32 v219, v195, v219
	v_fma_f32 v218, v141, v218, v138
	v_fma_f32 v219, v139, v219, v140
	v_mul_f32_e32 v218, 0x3fd744fd, v218
	v_mul_f32_e32 v219, 0x3fd744fd, v219
	v_fmac_f32_e32 v218, v61, v137
	v_fmac_f32_e32 v219, v45, v136
	global_store_dword v207, v218, s[20:21]
	global_store_dword v207, v219, s[20:21] offset:128
	s_waitcnt vmcnt(14)
	v_sub_f32_e32 v220, v220, v196
	v_sub_f32_e32 v221, v221, v196
	v_mul_f32_e32 v220, v197, v220
	v_mul_f32_e32 v221, v197, v221
	v_fma_f32 v220, v141, v220, v138
	v_fma_f32 v221, v139, v221, v140
	v_mul_f32_e32 v220, 0x3fd744fd, v220
	v_mul_f32_e32 v221, 0x3fd744fd, v221
	v_fmac_f32_e32 v220, v62, v137
	v_fmac_f32_e32 v221, v46, v136
	global_store_dword v208, v220, s[20:21]
	global_store_dword v208, v221, s[20:21] offset:128
	s_waitcnt vmcnt(14)
	v_sub_f32_e32 v222, v222, v198
	v_sub_f32_e32 v223, v223, v198
	v_mul_f32_e32 v222, v199, v222
	v_mul_f32_e32 v223, v199, v223
	v_fma_f32 v222, v141, v222, v138
	v_fma_f32 v223, v139, v223, v140
	v_mul_f32_e32 v222, 0x3fd744fd, v222
	v_mul_f32_e32 v223, 0x3fd744fd, v223
	v_fmac_f32_e32 v222, v63, v137
	v_fmac_f32_e32 v223, v47, v136
	global_store_dword v209, v222, s[20:21]
	global_store_dword v209, v223, s[20:21] offset:128
	s_waitcnt vmcnt(14)
	v_sub_f32_e32 v224, v224, v200
	v_sub_f32_e32 v225, v225, v200
	v_mul_f32_e32 v224, v201, v224
	v_mul_f32_e32 v225, v201, v225
	v_fma_f32 v224, v141, v224, v138
	v_fma_f32 v225, v139, v225, v140
	v_mul_f32_e32 v224, 0x3fd744fd, v224
	v_mul_f32_e32 v225, 0x3fd744fd, v225
	v_fmac_f32_e32 v224, v64, v137
	v_fmac_f32_e32 v225, v48, v136
	global_store_dword v210, v224, s[20:21]
	global_store_dword v210, v225, s[20:21] offset:128
	s_waitcnt vmcnt(14)
	v_sub_f32_e32 v226, v226, v202
	v_sub_f32_e32 v227, v227, v202
	v_mul_f32_e32 v226, v203, v226
	v_mul_f32_e32 v227, v203, v227
	v_fma_f32 v226, v141, v226, v138
	v_fma_f32 v227, v139, v227, v140
	v_mul_f32_e32 v226, 0x3fd744fd, v226
	v_mul_f32_e32 v227, 0x3fd744fd, v227
	v_fmac_f32_e32 v226, v65, v137
	v_fmac_f32_e32 v227, v49, v136
	global_store_dword v211, v226, s[20:21]
	global_store_dword v211, v227, s[20:21] offset:128
	v_mov_b32_e32 v188, 0
	v_mov_b32_e32 v189, 1.0
	v_mov_b32_e32 v190, 0
	v_mov_b32_e32 v191, 1.0
	v_mov_b32_e32 v192, 0
	v_mov_b32_e32 v193, 1.0
	v_mov_b32_e32 v194, 0
	v_mov_b32_e32 v195, 1.0
	v_mov_b32_e32 v196, 0
	v_mov_b32_e32 v197, 1.0
	v_mov_b32_e32 v198, 0
	v_mov_b32_e32 v199, 1.0
	v_mov_b32_e32 v200, 0
	v_mov_b32_e32 v201, 1.0
	v_mov_b32_e32 v202, 0
	v_mov_b32_e32 v203, 1.0
	s_and_b64 vcc, exec, s[38:39]
	s_cbranch_vccnz .Lres77_ns2
	global_load_dwordx4 v[188:191], v[130:131], off offset:256
	global_load_dwordx4 v[192:195], v[130:131], off offset:272
	global_load_dwordx4 v[196:199], v[130:131], off offset:320
	global_load_dwordx4 v[200:203], v[130:131], off offset:336
.Lres77_ns2:
	v_or_b32_e32 v204, 0x20000, v32
	global_load_dword v212, v204, s[0:1]
	global_load_dword v213, v204, s[0:1] offset:128
	v_or_b32_e32 v205, 0x21000, v32
	global_load_dword v214, v205, s[0:1]
	global_load_dword v215, v205, s[0:1] offset:128
	v_or_b32_e32 v206, 0x22000, v32
	global_load_dword v216, v206, s[0:1]
	global_load_dword v217, v206, s[0:1] offset:128
	v_or_b32_e32 v207, 0x23000, v32
	global_load_dword v218, v207, s[0:1]
	global_load_dword v219, v207, s[0:1] offset:128
	v_or_b32_e32 v208, 0x28000, v32
	global_load_dword v220, v208, s[0:1]
	global_load_dword v221, v208, s[0:1] offset:128
	v_or_b32_e32 v209, 0x29000, v32
	global_load_dword v222, v209, s[0:1]
	global_load_dword v223, v209, s[0:1] offset:128
	v_or_b32_e32 v210, 0x2a000, v32
	global_load_dword v224, v210, s[0:1]
	global_load_dword v225, v210, s[0:1] offset:128
	v_or_b32_e32 v211, 0x2b000, v32
	global_load_dword v226, v211, s[0:1]
	global_load_dword v227, v211, s[0:1] offset:128
	s_waitcnt vmcnt(14)
	v_sub_f32_e32 v212, v212, v188
	v_sub_f32_e32 v213, v213, v188
	v_mul_f32_e32 v212, v189, v212
	v_mul_f32_e32 v213, v189, v213
	v_fma_f32 v212, v141, v212, v138
	v_fma_f32 v213, v139, v213, v140
	v_mul_f32_e32 v212, 0x3fd744fd, v212
	v_mul_f32_e32 v213, 0x3fd744fd, v213
	v_fmac_f32_e32 v212, v16, v137
	v_fmac_f32_e32 v213, v0, v136
	global_store_dword v204, v212, s[20:21]
	global_store_dword v204, v213, s[20:21] offset:128
	s_waitcnt vmcnt(14)
	v_sub_f32_e32 v214, v214, v190
	v_sub_f32_e32 v215, v215, v190
	v_mul_f32_e32 v214, v191, v214
	v_mul_f32_e32 v215, v191, v215
	v_fma_f32 v214, v141, v214, v138
	v_fma_f32 v215, v139, v215, v140
	v_mul_f32_e32 v214, 0x3fd744fd, v214
	v_mul_f32_e32 v215, 0x3fd744fd, v215
	v_fmac_f32_e32 v214, v17, v137
	v_fmac_f32_e32 v215, v1, v136
	global_store_dword v205, v214, s[20:21]
	global_store_dword v205, v215, s[20:21] offset:128
	s_waitcnt vmcnt(14)
	v_sub_f32_e32 v216, v216, v192
	v_sub_f32_e32 v217, v217, v192
	v_mul_f32_e32 v216, v193, v216
	v_mul_f32_e32 v217, v193, v217
	v_fma_f32 v216, v141, v216, v138
	v_fma_f32 v217, v139, v217, v140
	v_mul_f32_e32 v216, 0x3fd744fd, v216
	v_mul_f32_e32 v217, 0x3fd744fd, v217
	v_fmac_f32_e32 v216, v18, v137
	v_fmac_f32_e32 v217, v2, v136
	global_store_dword v206, v216, s[20:21]
	global_store_dword v206, v217, s[20:21] offset:128
	s_waitcnt vmcnt(14)
	v_sub_f32_e32 v218, v218, v194
	v_sub_f32_e32 v219, v219, v194
	v_mul_f32_e32 v218, v195, v218
	v_mul_f32_e32 v219, v195, v219
	v_fma_f32 v218, v141, v218, v138
	v_fma_f32 v219, v139, v219, v140
	v_mul_f32_e32 v218, 0x3fd744fd, v218
	v_mul_f32_e32 v219, 0x3fd744fd, v219
	v_fmac_f32_e32 v218, v19, v137
	v_fmac_f32_e32 v219, v3, v136
	global_store_dword v207, v218, s[20:21]
	global_store_dword v207, v219, s[20:21] offset:128
	s_waitcnt vmcnt(14)
	v_sub_f32_e32 v220, v220, v196
	v_sub_f32_e32 v221, v221, v196
	v_mul_f32_e32 v220, v197, v220
	v_mul_f32_e32 v221, v197, v221
	v_fma_f32 v220, v141, v220, v138
	v_fma_f32 v221, v139, v221, v140
	v_mul_f32_e32 v220, 0x3fd744fd, v220
	v_mul_f32_e32 v221, 0x3fd744fd, v221
	v_fmac_f32_e32 v220, v20, v137
	v_fmac_f32_e32 v221, v4, v136
	global_store_dword v208, v220, s[20:21]
	global_store_dword v208, v221, s[20:21] offset:128
	s_waitcnt vmcnt(14)
	v_sub_f32_e32 v222, v222, v198
	v_sub_f32_e32 v223, v223, v198
	v_mul_f32_e32 v222, v199, v222
	v_mul_f32_e32 v223, v199, v223
	v_fma_f32 v222, v141, v222, v138
	v_fma_f32 v223, v139, v223, v140
	v_mul_f32_e32 v222, 0x3fd744fd, v222
	v_mul_f32_e32 v223, 0x3fd744fd, v223
	v_fmac_f32_e32 v222, v21, v137
	v_fmac_f32_e32 v223, v5, v136
	global_store_dword v209, v222, s[20:21]
	global_store_dword v209, v223, s[20:21] offset:128
	s_waitcnt vmcnt(14)
	v_sub_f32_e32 v224, v224, v200
	v_sub_f32_e32 v225, v225, v200
	v_mul_f32_e32 v224, v201, v224
	v_mul_f32_e32 v225, v201, v225
	v_fma_f32 v224, v141, v224, v138
	v_fma_f32 v225, v139, v225, v140
	v_mul_f32_e32 v224, 0x3fd744fd, v224
	v_mul_f32_e32 v225, 0x3fd744fd, v225
	v_fmac_f32_e32 v224, v22, v137
	v_fmac_f32_e32 v225, v6, v136
	global_store_dword v210, v224, s[20:21]
	global_store_dword v210, v225, s[20:21] offset:128
	s_waitcnt vmcnt(14)
	v_sub_f32_e32 v226, v226, v202
	v_sub_f32_e32 v227, v227, v202
	v_mul_f32_e32 v226, v203, v226
	v_mul_f32_e32 v227, v203, v227
	v_fma_f32 v226, v141, v226, v138
	v_fma_f32 v227, v139, v227, v140
	v_mul_f32_e32 v226, 0x3fd744fd, v226
	v_mul_f32_e32 v227, 0x3fd744fd, v227
	v_fmac_f32_e32 v226, v23, v137
	v_fmac_f32_e32 v227, v7, v136
	global_store_dword v211, v226, s[20:21]
	global_store_dword v211, v227, s[20:21] offset:128
	v_mov_b32_e32 v188, 0
	v_mov_b32_e32 v189, 1.0
	v_mov_b32_e32 v190, 0
	v_mov_b32_e32 v191, 1.0
	v_mov_b32_e32 v192, 0
	v_mov_b32_e32 v193, 1.0
	v_mov_b32_e32 v194, 0
	v_mov_b32_e32 v195, 1.0
	v_mov_b32_e32 v196, 0
	v_mov_b32_e32 v197, 1.0
	v_mov_b32_e32 v198, 0
	v_mov_b32_e32 v199, 1.0
	v_mov_b32_e32 v200, 0
	v_mov_b32_e32 v201, 1.0
	v_mov_b32_e32 v202, 0
	v_mov_b32_e32 v203, 1.0
	s_and_b64 vcc, exec, s[38:39]
	s_cbranch_vccnz .Lres77_ns3
	global_load_dwordx4 v[188:191], v[130:131], off offset:384
	global_load_dwordx4 v[192:195], v[130:131], off offset:400
	global_load_dwordx4 v[196:199], v[130:131], off offset:448
	global_load_dwordx4 v[200:203], v[130:131], off offset:464
